# no store drain at the end of P2b before P3's setup and first DMAs (LDS wait and workgroup barrier kept)
# baseline (speedup 1.0000x reference)
;     __device__ __forceinline__ bool next(int i, Unit& o) const { if (i) return false; o = u; return true; }
;     __host__ __device__ bool next(int i, Unit& u) const {
;         const long L = (long)i * G + c; if (L >= nwg) return false;
;         int wgid = (int)L; { const int q = nwg / NXCD, r = nwg % NXCD, xcd = wgid % NXCD, off = wgid / NXCD; wgid = (xcd < r ? xcd * (q + 1) : r * (q + 1) + (xcd - r) * q) + off; }
; __global__ void __launch_bounds__(NWAVES * 64, 2) mk_fwd(Args args) {
;     ...
;         asm volatile("s_waitcnt vmcnt(0)" ::: "memory");
;         __syncthreads();
;     }
;     {
;         pg8::AddrF2 g{trig2, zt}; pg8::StaticOrder S; S.init(64 * 256, 1024, G, (int)blockIdx.x);
.LBB0_518:
	s_mov_b32 s0, -1
	s_waitcnt lgkmcnt(0)
	s_barrier
	s_cmpk_lt_i32 s2, 0x100
	v_mbcnt_lo_u32_b32 v0, s0, 0
	v_mbcnt_hi_u32_b32 v4, s0, v0
	s_cselect_b64 s[0:1], -1, 0
	v_writelane_b32 v254, s0, 34
	s_cmpk_gt_i32 s2, 0xff
	s_nop 0
	v_writelane_b32 v254, s1, 35
	s_cbranch_scc1 .LBB0_544
	s_ashr_i32 s14, s2, 31
	s_lshr_b32 s0, s14, 29
	s_add_i32 s5, s2, s0
	s_and_b32 s0, s5, -8
	s_sub_i32 s6, s2, s0
	s_cmp_gt_i32 s6, -1
	s_cbranch_scc0 .LBB0_521
	s_lshl_b32 s4, s6, 5
	s_cbranch_execz .LBB0_522
	s_branch .LBB0_523
